# ranking sort keeps only the top 16 (20 stages), cross-row exchanges via v_permlane16/32_swap: no LDS round trip inside the sort
# speedup vs baseline: 1.0096x; 1.0024x over previous
.LBB0_328:
	v_ashrrev_i32_e32 v117, 31, v116
	v_lshlrev_b64 v[0:1], 11, v[116:117]
	v_lshl_add_u64 v[134:135], v[122:123], 0, v[0:1]
	global_load_dwordx4 v[12:15], v[134:135], off
	global_load_dwordx4 v[0:3], v[134:135], off offset:16
	v_readlane_b32 s2, v249, 30
	v_readlane_b32 s3, v249, 31
	s_load_dwordx2 s[2:3], s[2:3], 0x180
	v_lshlrev_b64 v[136:137], 10, v[116:117]
	v_mov_b32_e32 v131, v80
	v_mov_b32_e32 v133, v80
	s_movk_i32 s43, 0x80
	s_waitcnt lgkmcnt(0)
	v_lshl_add_u64 v[4:5], s[2:3], 0, v[136:137]
	v_lshl_add_u64 v[4:5], s[58:59], 0, v[4:5]
	v_lshl_add_u64 v[18:19], v[4:5], 0, v[130:131]
	v_lshl_add_u64 v[16:17], v[4:5], 0, v[132:133]
	global_load_dword v26, v[16:17], off offset:64
	global_load_dword v28, v[18:19], off
	global_load_dword v25, v[16:17], off offset:192
	global_load_dword v27, v[18:19], off offset:128
	global_load_dwordx4 v[4:7], v[134:135], off offset:48
	global_load_dwordx4 v[8:11], v[134:135], off offset:32
	global_load_dword v21, v[18:19], off offset:256
	global_load_dword v23, v[18:19], off offset:384
	global_load_dword v22, v[18:19], off offset:512
	global_load_dword v24, v[18:19], off offset:640
	global_load_dword v20, v[18:19], off offset:768
	s_nop 0
	global_load_dword v18, v[18:19], off offset:896
	s_nop 0
	global_load_dword v117, v[16:17], off offset:320
	global_load_dword v31, v[16:17], off offset:448
	global_load_dword v30, v[16:17], off offset:576
	global_load_dword v29, v[16:17], off offset:704
	global_load_dword v19, v[16:17], off offset:832
	s_nop 0
	global_load_dword v16, v[16:17], off offset:960
	s_movk_i32 s44, 0x3f80
	v_mov_b32_e32 v176, 0
	v_mov_b32_e32 v177, v176
	v_mov_b32_e32 v216, v176
	v_mov_b32_e32 v217, v176
	v_mov_b32_e32 v214, v176
	v_mov_b32_e32 v215, v176
	v_mov_b32_e32 v212, v176
	v_mov_b32_e32 v213, v176
	v_mov_b32_e32 v210, v176
	v_mov_b32_e32 v211, v176
	v_mov_b32_e32 v208, v176
	v_mov_b32_e32 v209, v176
	v_mov_b32_e32 v206, v176
	v_mov_b32_e32 v207, v176
	v_mov_b32_e32 v204, v176
	v_mov_b32_e32 v205, v176
	v_mov_b32_e32 v202, v176
	v_mov_b32_e32 v203, v176
	v_mov_b32_e32 v200, v176
	v_mov_b32_e32 v201, v176
	v_mov_b32_e32 v198, v176
	v_mov_b32_e32 v199, v176
	v_mov_b32_e32 v196, v176
	v_mov_b32_e32 v197, v176
	v_mov_b32_e32 v194, v176
	v_mov_b32_e32 v195, v176
	v_mov_b32_e32 v192, v176
	v_mov_b32_e32 v193, v176
	v_mov_b32_e32 v190, v176
	v_mov_b32_e32 v191, v176
	v_mov_b32_e32 v188, v176
	v_mov_b32_e32 v189, v176
	s_waitcnt vmcnt(17)
	v_cmp_lt_i32_e32 vcc, -1, v26
	s_waitcnt vmcnt(13)
	v_lshlrev_b32_e32 v160, 16, v4
	v_lshlrev_b32_e32 v152, 16, v12
	v_lshlrev_b32_e32 v174, 16, v1
	v_and_b32_e32 v143, 0xffff0000, v1
	v_cndmask_b32_e64 v1, v232, -1, vcc
	v_cmp_lt_i32_e32 vcc, -1, v28
	v_and_b32_e32 v150, 0xffff0000, v12
	v_lshlrev_b32_e32 v148, 16, v14
	v_cndmask_b32_e64 v12, v232, -1, vcc
	v_cmp_lt_i32_e32 vcc, -1, v25
	v_and_b32_e32 v146, 0xffff0000, v14
	v_lshlrev_b32_e32 v172, 16, v15
	v_cndmask_b32_e64 v17, v232, -1, vcc
	v_cmp_lt_i32_e32 vcc, -1, v27
	v_and_b32_e32 v147, 0xffff0000, v15
	v_lshlrev_b32_e32 v144, 16, v0
	v_and_b32_e32 v142, 0xffff0000, v0
	v_lshlrev_b32_e32 v140, 16, v2
	v_and_b32_e32 v138, 0xffff0000, v2
	v_and_b32_e32 v0, 0xffffff80, v26
	v_and_b32_e32 v2, 0xffffff80, v28
	v_and_b32_e32 v14, 0xffffff80, v25
	v_and_b32_e32 v15, 0xffffff80, v27
	v_cndmask_b32_e64 v32, v232, -1, vcc
	v_lshlrev_b32_e32 v170, 16, v13
	v_and_b32_e32 v151, 0xffff0000, v13
	v_xor_b32_e32 v1, v1, v0
	v_xor_b32_e32 v13, v12, v2
	v_xor_b32_e32 v0, v17, v14
	v_xor_b32_e32 v12, v32, v15
	v_pk_add_f32 v[0:1], v[12:13], v[0:1]
	v_lshlrev_b32_e32 v178, 16, v3
	v_or_b32_e32 v2, 0x80000000, v1
	v_not_b32_e32 v12, v1
	v_cmp_gt_i32_e32 vcc, 0, v1
	v_and_b32_e32 v139, 0xffff0000, v3
	s_waitcnt vmcnt(12)
	v_lshlrev_b32_e32 v168, 16, v8
	v_cndmask_b32_e32 v2, v2, v12, vcc
	v_and_b32_e32 v2, 0xffffffc0, v2
	v_bitop3_b32 v2, v2, 63, v81 bitop3:0x36
	v_cndmask_b32_e64 v2, 0, v2, s[10:11]
	v_and_b32_e32 v166, 0xffff0000, v8
	v_readlane_b32 s3, v2, 1
	v_readlane_b32 s24, v2, 2
	v_readlane_b32 s26, v2, 4
	v_cmp_gt_u32_e32 vcc, s3, v2
	v_readlane_b32 s30, v2, 6
	v_readlane_b32 s34, v2, 8
	v_cndmask_b32_e64 v12, 0, 1, vcc
	v_cmp_gt_u32_e32 vcc, s24, v2
	v_readlane_b32 s2, v2, 0
	v_readlane_b32 s25, v2, 3
	v_cndmask_b32_e64 v13, 0, 1, vcc
	v_cmp_gt_u32_e32 vcc, s26, v2
	v_readlane_b32 s27, v2, 5
	v_readlane_b32 s31, v2, 7
	v_cndmask_b32_e64 v14, 0, 1, vcc
	v_cmp_gt_u32_e32 vcc, s30, v2
	v_and_b32_e32 v158, 0xffff0000, v4
	v_lshlrev_b32_e32 v184, 16, v5
	v_cndmask_b32_e64 v15, 0, 1, vcc
	v_cmp_gt_u32_e32 vcc, s34, v2
	v_and_b32_e32 v159, 0xffff0000, v5
	v_lshlrev_b32_e32 v156, 16, v6
	v_cndmask_b32_e64 v17, 0, 1, vcc
	v_cmp_gt_u32_e32 vcc, s2, v2
	v_readlane_b32 s2, v2, 9
	v_and_b32_e32 v154, 0xffff0000, v6
	v_addc_co_u32_e32 v12, vcc, 0, v12, vcc
	v_cmp_gt_u32_e32 vcc, s25, v2
	v_lshlrev_b32_e32 v5, 7, v28
	v_and_b32_e32 v6, 0x7f, v26
	v_addc_co_u32_e32 v12, vcc, v12, v13, vcc
	v_cmp_gt_u32_e32 vcc, s27, v2
	v_and_or_b32 v5, v5, s44, v6
	v_lshlrev_b32_e32 v186, 16, v7
	v_addc_co_u32_e32 v12, vcc, v12, v14, vcc
	v_cmp_gt_u32_e32 vcc, s31, v2
	v_and_b32_e32 v155, 0xffff0000, v7
	v_lshlrev_b32_e32 v164, 16, v10
	v_addc_co_u32_e32 v12, vcc, v12, v15, vcc
	v_cmp_gt_u32_e32 vcc, s2, v2
	v_readlane_b32 s2, v2, 10
	v_and_b32_e32 v162, 0xffff0000, v10
	v_addc_co_u32_e32 v12, vcc, v12, v17, vcc
	v_cmp_gt_u32_e32 vcc, s2, v2
	v_readlane_b32 s2, v2, 11
	v_lshlrev_b32_e32 v182, 16, v11
	v_cndmask_b32_e64 v13, 0, 1, vcc
	v_cmp_gt_u32_e32 vcc, s2, v2
	v_readlane_b32 s2, v2, 12
	v_and_b32_e32 v163, 0xffff0000, v11
	v_addc_co_u32_e32 v12, vcc, v12, v13, vcc
	v_cmp_gt_u32_e32 vcc, s2, v2
	v_readlane_b32 s2, v2, 13
	v_not_b32_e32 v17, v0
	v_cndmask_b32_e64 v13, 0, 1, vcc
	v_cmp_gt_u32_e32 vcc, s2, v2
	v_readlane_b32 s2, v2, 14
	v_lshlrev_b32_e32 v180, 16, v9
	v_addc_co_u32_e32 v12, vcc, v12, v13, vcc
	v_cmp_gt_u32_e32 vcc, s2, v2
	v_readlane_b32 s2, v2, 15
	v_and_b32_e32 v167, 0xffff0000, v9
	v_cndmask_b32_e64 v13, 0, 1, vcc
	v_cmp_gt_u32_e32 vcc, s2, v2
	v_readlane_b32 s2, v2, 16
	v_and_b32_e32 v9, 0x7f, v25
	v_addc_co_u32_e32 v12, vcc, v12, v13, vcc
	v_cmp_gt_u32_e32 vcc, s2, v2
	v_readlane_b32 s2, v2, 17
	s_mov_b32 s24, 0
	v_cndmask_b32_e64 v13, 0, 1, vcc
	v_cmp_gt_u32_e32 vcc, s2, v2
	v_readlane_b32 s2, v2, 18
	v_mov_b32_e32 v153, v150
	v_addc_co_u32_e32 v12, vcc, v12, v13, vcc
	v_cmp_gt_u32_e32 vcc, s2, v2
	v_readlane_b32 s2, v2, 19
	v_mov_b32_e32 v171, v151
	v_cndmask_b32_e64 v13, 0, 1, vcc
	v_cmp_gt_u32_e32 vcc, s2, v2
	v_readlane_b32 s2, v2, 20
	v_mov_b32_e32 v149, v146
	v_addc_co_u32_e32 v12, vcc, v12, v13, vcc
	v_cmp_gt_u32_e32 vcc, s2, v2
	v_readlane_b32 s2, v2, 21
	v_mov_b32_e32 v173, v147
	v_cndmask_b32_e64 v13, 0, 1, vcc
	v_cmp_gt_u32_e32 vcc, s2, v2
	v_readlane_b32 s2, v2, 22
	v_mov_b32_e32 v145, v142
	v_addc_co_u32_e32 v12, vcc, v12, v13, vcc
	v_cmp_gt_u32_e32 vcc, s2, v2
	v_readlane_b32 s2, v2, 23
	v_mov_b32_e32 v175, v143
	v_cndmask_b32_e64 v13, 0, 1, vcc
	v_cmp_gt_u32_e32 vcc, s2, v2
	v_readlane_b32 s2, v2, 24
	v_mov_b32_e32 v141, v138
	v_addc_co_u32_e32 v12, vcc, v12, v13, vcc
	v_cmp_gt_u32_e32 vcc, s2, v2
	v_readlane_b32 s2, v2, 25
	v_mov_b32_e32 v179, v139
	v_cndmask_b32_e64 v13, 0, 1, vcc
	v_cmp_gt_u32_e32 vcc, s2, v2
	v_readlane_b32 s2, v2, 26
	v_mov_b32_e32 v169, v166
	v_addc_co_u32_e32 v12, vcc, v12, v13, vcc
	v_cmp_gt_u32_e32 vcc, s2, v2
	v_readlane_b32 s2, v2, 27
	v_mov_b32_e32 v181, v167
	v_cndmask_b32_e64 v13, 0, 1, vcc
	v_cmp_gt_u32_e32 vcc, s2, v2
	v_readlane_b32 s2, v2, 28
	v_mov_b32_e32 v165, v162
	v_addc_co_u32_e32 v12, vcc, v12, v13, vcc
	v_cmp_gt_u32_e32 vcc, s2, v2
	v_readlane_b32 s2, v2, 29
	v_mov_b32_e32 v183, v163
	v_cndmask_b32_e64 v13, 0, 1, vcc
	v_cmp_gt_u32_e32 vcc, s2, v2
	v_readlane_b32 s2, v2, 30
	v_mov_b32_e32 v161, v158
	v_addc_co_u32_e32 v12, vcc, v12, v13, vcc
	v_cmp_gt_u32_e32 vcc, s2, v2
	v_readlane_b32 s2, v2, 31
	v_mov_b32_e32 v185, v159
	v_cndmask_b32_e64 v13, 0, 1, vcc
	v_cmp_gt_u32_e32 vcc, s2, v2
	v_readlane_b32 s2, v2, 32
	v_mov_b32_e32 v157, v154
	v_addc_co_u32_e32 v12, vcc, v12, v13, vcc
	v_cmp_gt_u32_e32 vcc, s2, v2
	v_readlane_b32 s2, v2, 33
	v_mov_b32_e32 v187, v155
	v_cndmask_b32_e64 v13, 0, 1, vcc
	v_cmp_gt_u32_e32 vcc, s2, v2
	v_readlane_b32 s2, v2, 34
	s_nop 0
	v_addc_co_u32_e32 v12, vcc, v12, v13, vcc
	v_cmp_gt_u32_e32 vcc, s2, v2
	v_readlane_b32 s2, v2, 35
	s_nop 0
	v_cndmask_b32_e64 v13, 0, 1, vcc
	v_cmp_gt_u32_e32 vcc, s2, v2
	v_readlane_b32 s2, v2, 36
	s_nop 0
	v_addc_co_u32_e32 v12, vcc, v12, v13, vcc
	v_cmp_gt_u32_e32 vcc, s2, v2
	v_readlane_b32 s2, v2, 37
	s_nop 0
	v_cndmask_b32_e64 v13, 0, 1, vcc
	v_cmp_gt_u32_e32 vcc, s2, v2
	v_readlane_b32 s2, v2, 38
	s_nop 0
	v_addc_co_u32_e32 v12, vcc, v12, v13, vcc
	v_cmp_gt_u32_e32 vcc, s2, v2
	v_readlane_b32 s2, v2, 39
	s_nop 0
	v_cndmask_b32_e64 v13, 0, 1, vcc
	v_cmp_gt_u32_e32 vcc, s2, v2
	v_readlane_b32 s2, v2, 40
	s_nop 0
	v_addc_co_u32_e32 v12, vcc, v12, v13, vcc
	v_cmp_gt_u32_e32 vcc, s2, v2
	v_readlane_b32 s2, v2, 41
	s_nop 0
	v_cndmask_b32_e64 v13, 0, 1, vcc
	v_cmp_gt_u32_e32 vcc, s2, v2
	v_readlane_b32 s2, v2, 42
	s_nop 0
	v_addc_co_u32_e32 v12, vcc, v12, v13, vcc
	v_cmp_gt_u32_e32 vcc, s2, v2
	v_readlane_b32 s2, v2, 43
	s_nop 0
	v_cndmask_b32_e64 v13, 0, 1, vcc
	v_cmp_gt_u32_e32 vcc, s2, v2
	v_readlane_b32 s2, v2, 44
	s_nop 0
	v_addc_co_u32_e32 v12, vcc, v12, v13, vcc
	v_cmp_gt_u32_e32 vcc, s2, v2
	v_readlane_b32 s2, v2, 45
	s_nop 0
	v_cndmask_b32_e64 v13, 0, 1, vcc
	v_cmp_gt_u32_e32 vcc, s2, v2
	v_readlane_b32 s2, v2, 46
	s_nop 0
	v_addc_co_u32_e32 v12, vcc, v12, v13, vcc
	v_cmp_gt_u32_e32 vcc, s2, v2
	v_readlane_b32 s2, v2, 47
	s_nop 0
	v_cndmask_b32_e64 v13, 0, 1, vcc
	v_cmp_gt_u32_e32 vcc, s2, v2
	v_readlane_b32 s2, v2, 48
	s_nop 0
	v_addc_co_u32_e32 v12, vcc, v12, v13, vcc
	v_cmp_gt_u32_e32 vcc, s2, v2
	v_readlane_b32 s2, v2, 49
	s_nop 0
	v_cndmask_b32_e64 v13, 0, 1, vcc
	v_cmp_gt_u32_e32 vcc, s2, v2
	s_nop 1
	v_addc_co_u32_e32 v2, vcc, v12, v13, vcc
	v_lshlrev_b32_e32 v13, 3, v2
	v_lshlrev_b32_e32 v12, 7, v2
	v_and_b32_e32 v13, 0x70, v13
	v_and_or_b32 v12, v12, s43, v13
	v_cmp_gt_u32_e32 vcc, 16, v2
	s_nop 1
	v_cndmask_b32_e32 v2, 4, v12, vcc
	ds_permute_b32 v1, v2, v1
	ds_permute_b32 v2, v2, v5
	s_waitcnt lgkmcnt(1)
	v_readlane_b32 s2, v1, 0
	s_nop 1
	v_subrev_f32_e32 v1, s2, v1
	v_mul_f32_e32 v1, 0x3fb8aa3b, v1
	v_exp_f32_e32 v1, v1
	s_waitcnt lgkmcnt(0)
	v_readlane_b32 s25, v2, 4
	v_readlane_b32 s26, v2, 36
	v_readlane_b32 s27, v2, 8
	v_cndmask_b32_e64 v1, 0, v1, s[12:13]
	s_nop 1
	v_add_f32_dpp v254, v1, v1 quad_perm:[1,0,3,2] row_mask:0xf bank_mask:0xf
	s_nop 1
	v_add_f32_dpp v254, v254, v254 quad_perm:[2,3,0,1] row_mask:0xf bank_mask:0xf
	s_nop 1
	v_add_f32_dpp v254, v254, v254 row_half_mirror row_mask:0xf bank_mask:0xf
	s_nop 1
	v_add_f32_dpp v254, v254, v254 row_mirror row_mask:0xf bank_mask:0xf
	s_nop 1
	v_add_f32_dpp v254, v254, v254 row_bcast:15 row_mask:0xa bank_mask:0xf
	s_nop 1
	v_add_f32_dpp v254, v254, v254 row_bcast:31 row_mask:0xc bank_mask:0xf
	s_nop 1
	v_readlane_b32 s64, v254, 63
	v_readlane_b32 s30, v2, 40
	v_readlane_b32 s31, v2, 12
	v_readlane_b32 s34, v2, 44
	v_readlane_b32 s35, v2, 16
	s_waitcnt lgkmcnt(0)
	v_readlane_b32 s36, v2, 48
	v_readlane_b32 s37, v2, 20
	v_readlane_b32 s38, v2, 52
	v_readlane_b32 s39, v2, 24
	s_waitcnt lgkmcnt(0)
	v_readlane_b32 s40, v2, 56
	v_readlane_b32 s41, v2, 28
	v_readlane_b32 s42, v2, 60
	v_lshlrev_b32_e32 v8, 7, v27
	s_waitcnt lgkmcnt(0)
	v_and_or_b32 v8, v8, s44, v9
	s_waitcnt lgkmcnt(0)
	v_mov_b32_e32 v3, s64
	v_div_scale_f32 v4, s[2:3], v3, v3, v1
	v_rcp_f32_e32 v6, v4
	v_readlane_b32 s2, v2, 0
	v_readlane_b32 s3, v2, 32
	v_fma_f32 v5, -v4, v6, 1.0
	v_fmac_f32_e32 v6, v5, v6
	v_div_scale_f32 v5, vcc, v1, v3, v1
	v_mul_f32_e32 v7, v5, v6
	v_fma_f32 v10, -v4, v7, v5
	v_fmac_f32_e32 v7, v10, v6
	v_fma_f32 v4, -v4, v7, v5
	v_div_fmas_f32 v4, v4, v6, v7
	v_div_fixup_f32 v3, v4, v3, v1
	v_mov_b32_e32 v1, s2
	v_mov_b32_e32 v4, s3
	v_cndmask_b32_e64 v1, v1, v4, s[6:7]
	v_mad_i64_i32 v[4:5], s[2:3], v1, s28, v[118:119]
	global_load_dwordx2 v[36:37], v[4:5], off offset:16
	global_load_dwordx4 v[32:35], v[4:5], off
	v_mov_b32_e32 v4, s25
	v_mov_b32_e32 v5, s26
	v_cndmask_b32_e64 v6, v4, v5, s[6:7]
	v_mad_i64_i32 v[4:5], s[2:3], v6, s28, v[118:119]
	global_load_dwordx2 v[42:43], v[4:5], off offset:16
	global_load_dwordx4 v[38:41], v[4:5], off
	v_mov_b32_e32 v4, s27
	v_mov_b32_e32 v5, s30
	v_cndmask_b32_e64 v10, v4, v5, s[6:7]
	v_mad_i64_i32 v[4:5], s[2:3], v10, s28, v[118:119]
	global_load_dwordx2 v[48:49], v[4:5], off offset:16
	global_load_dwordx4 v[44:47], v[4:5], off
	v_mov_b32_e32 v4, s31
	v_mov_b32_e32 v5, s34
	v_cndmask_b32_e64 v11, v4, v5, s[6:7]
	v_mad_i64_i32 v[4:5], s[2:3], v11, s28, v[118:119]
	global_load_dwordx2 v[54:55], v[4:5], off offset:16
	global_load_dwordx4 v[50:53], v[4:5], off
	v_mov_b32_e32 v4, s35
	v_mov_b32_e32 v5, s36
	v_cndmask_b32_e64 v12, v4, v5, s[6:7]
	v_mad_i64_i32 v[4:5], s[2:3], v12, s28, v[118:119]
	global_load_dwordx2 v[60:61], v[4:5], off offset:16
	global_load_dwordx4 v[56:59], v[4:5], off
	v_mov_b32_e32 v4, s37
	v_mov_b32_e32 v5, s38
	v_cndmask_b32_e64 v13, v4, v5, s[6:7]
	v_mad_i64_i32 v[4:5], s[2:3], v13, s28, v[118:119]
	global_load_dwordx2 v[66:67], v[4:5], off offset:16
	global_load_dwordx4 v[62:65], v[4:5], off
	v_mov_b32_e32 v4, s39
	v_mov_b32_e32 v5, s40
	v_cndmask_b32_e64 v14, v4, v5, s[6:7]
	v_mad_i64_i32 v[4:5], s[2:3], v14, s28, v[118:119]
	global_load_dwordx2 v[72:73], v[4:5], off offset:16
	global_load_dwordx4 v[68:71], v[4:5], off
	v_mov_b32_e32 v4, s41
	v_mov_b32_e32 v5, s42
	v_cndmask_b32_e64 v15, v4, v5, s[6:7]
	v_mad_i64_i32 v[4:5], s[2:3], v15, s28, v[118:119]
	global_load_dwordx2 v[78:79], v[4:5], off offset:16
	global_load_dwordx4 v[74:77], v[4:5], off
	v_mad_i64_i32 v[4:5], s[2:3], v1, s28, v[120:121]
	v_or_b32_e32 v1, 0x80000000, v0
	v_cmp_gt_i32_e32 vcc, 0, v0
	v_mad_i64_i32 v[6:7], s[2:3], v6, s28, v[120:121]
	s_nop 0
	v_cndmask_b32_e32 v1, v1, v17, vcc
	v_and_b32_e32 v1, 0xffffffc0, v1
	v_cndmask_b32_e64 v1, 0, v1, s[10:11]
	v_bitop3_b32 v1, v1, 63, v81 bitop3:0x36
	global_load_dwordx4 v[110:113], v[4:5], off offset:768
	global_load_dwordx4 v[106:109], v[6:7], off offset:768
	s_mov_b32 vcc_lo, 0x55555555
	s_mov_b32 vcc_hi, 0x55555555
	s_mov_b32 s48, 0x33333333
	s_mov_b32 s49, 0x33333333
	v_max_u32_dpp v250, v1, v1 quad_perm:[1,0,3,2] row_mask:0xf bank_mask:0xf
	v_min_u32_dpp v251, v1, v1 quad_perm:[1,0,3,2] row_mask:0xf bank_mask:0xf
	v_cndmask_b32_e32 v17, v251, v250, vcc
	s_nop 1
	v_max_u32_dpp v250, v17, v17 quad_perm:[3,2,1,0] row_mask:0xf bank_mask:0xf
	v_min_u32_dpp v251, v17, v17 quad_perm:[3,2,1,0] row_mask:0xf bank_mask:0xf
	v_cndmask_b32_e64 v1, v251, v250, s[48:49]
	s_nop 1
	v_max_u32_dpp v250, v1, v1 quad_perm:[1,0,3,2] row_mask:0xf bank_mask:0xf
	v_min_u32_dpp v251, v1, v1 quad_perm:[1,0,3,2] row_mask:0xf bank_mask:0xf
	v_cndmask_b32_e32 v17, v251, v250, vcc
	s_nop 1
	v_max_u32_dpp v1, v17, v17 row_half_mirror row_mask:0xf bank_mask:0x5
	v_min_u32_dpp v1, v17, v17 row_half_mirror row_mask:0xf bank_mask:0xa
	s_nop 1
	v_max_u32_dpp v250, v1, v1 quad_perm:[2,3,0,1] row_mask:0xf bank_mask:0xf
	v_min_u32_dpp v251, v1, v1 quad_perm:[2,3,0,1] row_mask:0xf bank_mask:0xf
	v_cndmask_b32_e64 v17, v251, v250, s[48:49]
	s_nop 1
	v_max_u32_dpp v250, v17, v17 quad_perm:[1,0,3,2] row_mask:0xf bank_mask:0xf
	v_min_u32_dpp v251, v17, v17 quad_perm:[1,0,3,2] row_mask:0xf bank_mask:0xf
	v_cndmask_b32_e32 v1, v251, v250, vcc
	s_nop 1
	v_max_u32_dpp v17, v1, v1 row_mirror row_mask:0xf bank_mask:0x3
	v_min_u32_dpp v17, v1, v1 row_mirror row_mask:0xf bank_mask:0xc
	s_nop 1
	v_max_u32_dpp v1, v17, v17 row_ror:12 row_mask:0xf bank_mask:0x5
	v_min_u32_dpp v1, v17, v17 row_ror:4 row_mask:0xf bank_mask:0xa
	s_nop 1
	v_max_u32_dpp v250, v1, v1 quad_perm:[2,3,0,1] row_mask:0xf bank_mask:0xf
	v_min_u32_dpp v251, v1, v1 quad_perm:[2,3,0,1] row_mask:0xf bank_mask:0xf
	v_cndmask_b32_e64 v17, v251, v250, s[48:49]
	s_nop 1
	v_max_u32_dpp v250, v17, v17 quad_perm:[1,0,3,2] row_mask:0xf bank_mask:0xf
	v_min_u32_dpp v251, v17, v17 quad_perm:[1,0,3,2] row_mask:0xf bank_mask:0xf
	v_cndmask_b32_e32 v1, v251, v250, vcc
	s_nop 1
	v_mov_b32_dpp v250, v1 row_mirror row_mask:0xf bank_mask:0xf
	v_mov_b32_e32 v251, v250
	s_nop 0
	s_nop 0
	v_permlane16_swap_b32_e32 v250, v251
	s_nop 1
	v_max_u32_dpp v1, v251, v1 quad_perm:[0,1,2,3] row_mask:0x5 bank_mask:0xf
	v_min_u32_dpp v1, v250, v1 quad_perm:[0,1,2,3] row_mask:0xa bank_mask:0xf
	s_nop 1
	v_max_u32_dpp v17, v1, v1 row_ror:8 row_mask:0xf bank_mask:0x3
	v_min_u32_dpp v17, v1, v1 row_ror:8 row_mask:0xf bank_mask:0xc
	s_nop 1
	v_max_u32_dpp v1, v17, v17 row_ror:12 row_mask:0xf bank_mask:0x5
	v_min_u32_dpp v1, v17, v17 row_ror:4 row_mask:0xf bank_mask:0xa
	s_nop 1
	v_max_u32_dpp v250, v1, v1 quad_perm:[2,3,0,1] row_mask:0xf bank_mask:0xf
	v_min_u32_dpp v251, v1, v1 quad_perm:[2,3,0,1] row_mask:0xf bank_mask:0xf
	v_cndmask_b32_e64 v17, v251, v250, s[48:49]
	s_nop 1
	v_max_u32_dpp v250, v17, v17 quad_perm:[1,0,3,2] row_mask:0xf bank_mask:0xf
	v_min_u32_dpp v251, v17, v17 quad_perm:[1,0,3,2] row_mask:0xf bank_mask:0xf
	v_cndmask_b32_e32 v1, v251, v250, vcc
	s_nop 1
	v_mov_b32_dpp v250, v1 row_mirror row_mask:0xf bank_mask:0xf
	v_mov_b32_e32 v251, v250
	s_nop 1
	v_permlane32_swap_b32_e32 v251, v250
	s_nop 1
	v_max_u32_dpp v1, v250, v1 quad_perm:[0,1,2,3] row_mask:0x1 bank_mask:0xf
	v_min_u32_dpp v1, v251, v1 quad_perm:[0,1,2,3] row_mask:0x4 bank_mask:0xf
	s_nop 1
	v_max_u32_dpp v17, v1, v1 row_ror:8 row_mask:0xf bank_mask:0x3
	v_min_u32_dpp v17, v1, v1 row_ror:8 row_mask:0xf bank_mask:0xc
	s_nop 1
	v_max_u32_dpp v1, v17, v17 row_ror:12 row_mask:0xf bank_mask:0x5
	v_min_u32_dpp v1, v17, v17 row_ror:4 row_mask:0xf bank_mask:0xa
	s_nop 1
	v_max_u32_dpp v250, v1, v1 quad_perm:[2,3,0,1] row_mask:0xf bank_mask:0xf
	v_min_u32_dpp v251, v1, v1 quad_perm:[2,3,0,1] row_mask:0xf bank_mask:0xf
	v_cndmask_b32_e64 v17, v251, v250, s[48:49]
	s_nop 1
	v_max_u32_dpp v250, v17, v17 quad_perm:[1,0,3,2] row_mask:0xf bank_mask:0xf
	v_min_u32_dpp v251, v17, v17 quad_perm:[1,0,3,2] row_mask:0xf bank_mask:0xf
	v_cndmask_b32_e32 v1, v251, v250, vcc
	v_not_b32_e32 v253, v1
	v_and_b32_e32 v253, 63, v253
	v_lshlrev_b32_e32 v253, 2, v253
	ds_permute_b32 v1, v253, v81
	s_waitcnt lgkmcnt(0)
	v_lshlrev_b32_e32 v25, 3, v1
	v_lshlrev_b32_e32 v17, 7, v1
	v_and_b32_e32 v25, 0x70, v25
	v_and_or_b32 v17, v17, s43, v25
	v_cmp_gt_u32_e32 vcc, 16, v1
	s_nop 1
	v_cndmask_b32_e32 v17, 4, v17, vcc
	ds_permute_b32 v25, v17, v0
	v_mad_i64_i32 v[0:1], s[2:3], v10, s28, v[120:121]
	s_waitcnt vmcnt(23)
	v_cmp_lt_i32_e32 vcc, -1, v117
	s_waitcnt lgkmcnt(0)
	v_readlane_b32 s2, v25, 0
	s_nop 1
	v_subrev_f32_e32 v4, s2, v25
	v_mul_f32_e32 v4, 0x3fb8aa3b, v4
	v_exp_f32_e32 v6, v4
	v_mad_i64_i32 v[4:5], s[2:3], v11, s28, v[120:121]
	global_load_dwordx4 v[102:105], v[0:1], off offset:768
	global_load_dwordx4 v[98:101], v[4:5], off offset:768
	v_cndmask_b32_e64 v6, 0, v6, s[12:13]
	s_nop 1
	v_add_f32_dpp v254, v6, v6 quad_perm:[1,0,3,2] row_mask:0xf bank_mask:0xf
	s_nop 1
	v_add_f32_dpp v254, v254, v254 quad_perm:[2,3,0,1] row_mask:0xf bank_mask:0xf
	s_nop 1
	v_add_f32_dpp v254, v254, v254 row_half_mirror row_mask:0xf bank_mask:0xf
	s_nop 1
	v_add_f32_dpp v254, v254, v254 row_mirror row_mask:0xf bank_mask:0xf
	s_nop 1
	v_add_f32_dpp v254, v254, v254 row_bcast:15 row_mask:0xa bank_mask:0xf
	s_nop 1
	v_add_f32_dpp v254, v254, v254 row_bcast:31 row_mask:0xc bank_mask:0xf
	s_nop 1
	v_readlane_b32 s65, v254, 63
	v_mad_i64_i32 v[0:1], s[2:3], v12, s28, v[120:121]
	v_mad_i64_i32 v[4:5], s[2:3], v13, s28, v[120:121]
	s_waitcnt lgkmcnt(0)
	global_load_dwordx4 v[94:97], v[0:1], off offset:768
	global_load_dwordx4 v[90:93], v[4:5], off offset:768
	v_mad_i64_i32 v[0:1], s[2:3], v14, s28, v[120:121]
	v_mad_i64_i32 v[4:5], s[2:3], v15, s28, v[120:121]
	s_waitcnt lgkmcnt(0)
	global_load_dwordx4 v[86:89], v[0:1], off offset:768
	global_load_dwordx4 v[82:85], v[4:5], off offset:768
	v_cndmask_b32_e64 v1, v232, -1, vcc
	v_cmp_lt_i32_e32 vcc, -1, v21
	v_and_b32_e32 v0, 0xffffff80, v117
	s_waitcnt lgkmcnt(0)
	v_cndmask_b32_e64 v5, v232, -1, vcc
	s_waitcnt vmcnt(28)
	v_cmp_lt_i32_e32 vcc, -1, v31
	v_and_b32_e32 v4, 0xffffff80, v21
	v_xor_b32_e32 v1, v1, v0
	v_cndmask_b32_e64 v10, v232, -1, vcc
	v_cmp_lt_i32_e32 vcc, -1, v23
	v_xor_b32_e32 v5, v5, v4
	v_and_b32_e32 v0, 0xffffff80, v31
	v_and_b32_e32 v4, 0xffffff80, v23
	v_cndmask_b32_e64 v11, v232, -1, vcc
	v_xor_b32_e32 v0, v10, v0
	v_xor_b32_e32 v4, v11, v4
	v_pk_add_f32 v[0:1], v[4:5], v[0:1]
	v_or_b32_e32 v4, 0x80000000, v1
	v_not_b32_e32 v5, v1
	v_cmp_gt_i32_e32 vcc, 0, v1
	s_nop 1
	v_cndmask_b32_e32 v4, v4, v5, vcc
	v_and_b32_e32 v4, 0xffffffc0, v4
	v_cndmask_b32_e64 v4, 0, v4, s[10:11]
	v_bitop3_b32 v4, v4, 63, v81 bitop3:0x36
	s_nop 0
	s_mov_b32 vcc_lo, 0x55555555
	s_mov_b32 vcc_hi, 0x55555555
	s_mov_b32 s48, 0x33333333
	s_mov_b32 s49, 0x33333333
	v_max_u32_dpp v250, v4, v4 quad_perm:[1,0,3,2] row_mask:0xf bank_mask:0xf
	v_min_u32_dpp v251, v4, v4 quad_perm:[1,0,3,2] row_mask:0xf bank_mask:0xf
	v_cndmask_b32_e32 v5, v251, v250, vcc
	s_nop 1
	v_max_u32_dpp v250, v5, v5 quad_perm:[3,2,1,0] row_mask:0xf bank_mask:0xf
	v_min_u32_dpp v251, v5, v5 quad_perm:[3,2,1,0] row_mask:0xf bank_mask:0xf
	v_cndmask_b32_e64 v4, v251, v250, s[48:49]
	s_nop 1
	v_max_u32_dpp v250, v4, v4 quad_perm:[1,0,3,2] row_mask:0xf bank_mask:0xf
	v_min_u32_dpp v251, v4, v4 quad_perm:[1,0,3,2] row_mask:0xf bank_mask:0xf
	v_cndmask_b32_e32 v5, v251, v250, vcc
	s_nop 1
	v_max_u32_dpp v4, v5, v5 row_half_mirror row_mask:0xf bank_mask:0x5
	v_min_u32_dpp v4, v5, v5 row_half_mirror row_mask:0xf bank_mask:0xa
	s_nop 1
	v_max_u32_dpp v250, v4, v4 quad_perm:[2,3,0,1] row_mask:0xf bank_mask:0xf
	v_min_u32_dpp v251, v4, v4 quad_perm:[2,3,0,1] row_mask:0xf bank_mask:0xf
	v_cndmask_b32_e64 v5, v251, v250, s[48:49]
	s_nop 1
	v_max_u32_dpp v250, v5, v5 quad_perm:[1,0,3,2] row_mask:0xf bank_mask:0xf
	v_min_u32_dpp v251, v5, v5 quad_perm:[1,0,3,2] row_mask:0xf bank_mask:0xf
	v_cndmask_b32_e32 v4, v251, v250, vcc
	s_nop 1
	v_max_u32_dpp v5, v4, v4 row_mirror row_mask:0xf bank_mask:0x3
	v_min_u32_dpp v5, v4, v4 row_mirror row_mask:0xf bank_mask:0xc
	s_nop 1
	v_max_u32_dpp v4, v5, v5 row_ror:12 row_mask:0xf bank_mask:0x5
	v_min_u32_dpp v4, v5, v5 row_ror:4 row_mask:0xf bank_mask:0xa
	s_nop 1
	v_max_u32_dpp v250, v4, v4 quad_perm:[2,3,0,1] row_mask:0xf bank_mask:0xf
	v_min_u32_dpp v251, v4, v4 quad_perm:[2,3,0,1] row_mask:0xf bank_mask:0xf
	v_cndmask_b32_e64 v5, v251, v250, s[48:49]
	s_nop 1
	v_max_u32_dpp v250, v5, v5 quad_perm:[1,0,3,2] row_mask:0xf bank_mask:0xf
	v_min_u32_dpp v251, v5, v5 quad_perm:[1,0,3,2] row_mask:0xf bank_mask:0xf
	v_cndmask_b32_e32 v4, v251, v250, vcc
	s_nop 1
	v_mov_b32_dpp v250, v4 row_mirror row_mask:0xf bank_mask:0xf
	v_mov_b32_e32 v251, v250
	s_nop 0
	s_nop 0
	v_permlane16_swap_b32_e32 v250, v251
	s_nop 1
	v_max_u32_dpp v4, v251, v4 quad_perm:[0,1,2,3] row_mask:0x5 bank_mask:0xf
	v_min_u32_dpp v4, v250, v4 quad_perm:[0,1,2,3] row_mask:0xa bank_mask:0xf
	s_nop 1
	v_max_u32_dpp v5, v4, v4 row_ror:8 row_mask:0xf bank_mask:0x3
	v_min_u32_dpp v5, v4, v4 row_ror:8 row_mask:0xf bank_mask:0xc
	s_nop 1
	v_max_u32_dpp v4, v5, v5 row_ror:12 row_mask:0xf bank_mask:0x5
	v_min_u32_dpp v4, v5, v5 row_ror:4 row_mask:0xf bank_mask:0xa
	s_nop 1
	v_max_u32_dpp v250, v4, v4 quad_perm:[2,3,0,1] row_mask:0xf bank_mask:0xf
	v_min_u32_dpp v251, v4, v4 quad_perm:[2,3,0,1] row_mask:0xf bank_mask:0xf
	v_cndmask_b32_e64 v5, v251, v250, s[48:49]
	s_nop 1
	v_max_u32_dpp v250, v5, v5 quad_perm:[1,0,3,2] row_mask:0xf bank_mask:0xf
	v_min_u32_dpp v251, v5, v5 quad_perm:[1,0,3,2] row_mask:0xf bank_mask:0xf
	v_cndmask_b32_e32 v4, v251, v250, vcc
	s_nop 1
	v_mov_b32_dpp v250, v4 row_mirror row_mask:0xf bank_mask:0xf
	v_mov_b32_e32 v251, v250
	s_nop 1
	v_permlane32_swap_b32_e32 v251, v250
	s_nop 1
	v_max_u32_dpp v4, v250, v4 quad_perm:[0,1,2,3] row_mask:0x1 bank_mask:0xf
	v_min_u32_dpp v4, v251, v4 quad_perm:[0,1,2,3] row_mask:0x4 bank_mask:0xf
	s_nop 1
	v_max_u32_dpp v5, v4, v4 row_ror:8 row_mask:0xf bank_mask:0x3
	v_min_u32_dpp v5, v4, v4 row_ror:8 row_mask:0xf bank_mask:0xc
	s_nop 1
	v_max_u32_dpp v4, v5, v5 row_ror:12 row_mask:0xf bank_mask:0x5
	v_min_u32_dpp v4, v5, v5 row_ror:4 row_mask:0xf bank_mask:0xa
	s_nop 1
	v_max_u32_dpp v250, v4, v4 quad_perm:[2,3,0,1] row_mask:0xf bank_mask:0xf
	v_min_u32_dpp v251, v4, v4 quad_perm:[2,3,0,1] row_mask:0xf bank_mask:0xf
	v_cndmask_b32_e64 v5, v251, v250, s[48:49]
	s_nop 1
	v_max_u32_dpp v250, v5, v5 quad_perm:[1,0,3,2] row_mask:0xf bank_mask:0xf
	v_min_u32_dpp v251, v5, v5 quad_perm:[1,0,3,2] row_mask:0xf bank_mask:0xf
	v_cndmask_b32_e32 v4, v251, v250, vcc
	v_not_b32_e32 v253, v4
	v_and_b32_e32 v253, 63, v253
	v_lshlrev_b32_e32 v253, 2, v253
	ds_permute_b32 v4, v253, v81
	s_waitcnt lgkmcnt(0)
	v_lshlrev_b32_e32 v10, 3, v4
	v_lshlrev_b32_e32 v5, 7, v4
	v_and_b32_e32 v10, 0x70, v10
	v_and_or_b32 v5, v5, s43, v10
	v_cmp_gt_u32_e32 vcc, 16, v4
	ds_permute_b32 v4, v17, v8
	s_nop 0
	v_cndmask_b32_e32 v10, 4, v5, vcc
	ds_permute_b32 v1, v10, v1
	s_waitcnt lgkmcnt(2)
	v_mov_b32_e32 v5, s65
	v_div_scale_f32 v7, s[2:3], v5, v5, v6
	v_rcp_f32_e32 v9, v7
	s_waitcnt lgkmcnt(0)
	v_readlane_b32 s2, v1, 0
	v_div_scale_f32 v11, vcc, v6, v5, v6
	s_nop 0
	v_subrev_f32_e32 v1, s2, v1
	v_mul_f32_e32 v1, 0x3fb8aa3b, v1
	v_exp_f32_e32 v1, v1
	v_fma_f32 v8, -v7, v9, 1.0
	v_fmac_f32_e32 v9, v8, v9
	v_mul_f32_e32 v12, v11, v9
	v_cndmask_b32_e64 v1, 0, v1, s[12:13]
	s_nop 1
	v_add_f32_dpp v254, v1, v1 quad_perm:[1,0,3,2] row_mask:0xf bank_mask:0xf
	s_nop 1
	v_add_f32_dpp v254, v254, v254 quad_perm:[2,3,0,1] row_mask:0xf bank_mask:0xf
	s_nop 1
	v_add_f32_dpp v254, v254, v254 row_half_mirror row_mask:0xf bank_mask:0xf
	s_nop 1
	v_add_f32_dpp v254, v254, v254 row_mirror row_mask:0xf bank_mask:0xf
	s_nop 1
	v_add_f32_dpp v254, v254, v254 row_bcast:15 row_mask:0xa bank_mask:0xf
	s_nop 1
	v_add_f32_dpp v254, v254, v254 row_bcast:31 row_mask:0xc bank_mask:0xf
	s_nop 1
	v_readlane_b32 s64, v254, 63
	v_fma_f32 v13, -v7, v12, v11
	v_fmac_f32_e32 v12, v13, v9
	v_fma_f32 v7, -v7, v12, v11
	v_div_fmas_f32 v7, v7, v9, v12
	s_waitcnt lgkmcnt(0)
	v_div_fixup_f32 v5, v7, v5, v6
	v_or_b32_e32 v6, 0x80000000, v0
	v_not_b32_e32 v7, v0
	v_cmp_gt_i32_e32 vcc, 0, v0
	s_waitcnt lgkmcnt(0)
	v_cndmask_b32_e32 v6, v6, v7, vcc
	v_and_b32_e32 v6, 0xffffffc0, v6
	v_cndmask_b32_e64 v6, 0, v6, s[10:11]
	v_bitop3_b32 v6, v6, 63, v81 bitop3:0x36
	ds_write2st64_b64 v239, v[2:3], v[4:5] offset1:1
	s_cmp_lg_u32 s54, 0
	s_cbranch_scc1 .Lg_selskip
	s_mov_b32 vcc_lo, 0x55555555
	s_waitcnt lgkmcnt(1)
	s_mov_b32 vcc_hi, 0x55555555
	s_mov_b32 s48, 0x33333333
	s_mov_b32 s49, 0x33333333
	v_lshlrev_b32_e32 v2, 7, v21
	v_max_u32_dpp v250, v6, v6 quad_perm:[1,0,3,2] row_mask:0xf bank_mask:0xf
	v_min_u32_dpp v251, v6, v6 quad_perm:[1,0,3,2] row_mask:0xf bank_mask:0xf
	v_cndmask_b32_e32 v7, v251, v250, vcc
	v_and_b32_e32 v3, 0x7f, v117
	s_nop 1
	v_max_u32_dpp v250, v7, v7 quad_perm:[3,2,1,0] row_mask:0xf bank_mask:0xf
	v_min_u32_dpp v251, v7, v7 quad_perm:[3,2,1,0] row_mask:0xf bank_mask:0xf
	v_and_or_b32 v2, v2, s44, v3
	v_cndmask_b32_e64 v6, v251, v250, s[48:49]
	s_nop 1
	v_max_u32_dpp v250, v6, v6 quad_perm:[1,0,3,2] row_mask:0xf bank_mask:0xf
	s_waitcnt lgkmcnt(0)
	v_min_u32_dpp v251, v6, v6 quad_perm:[1,0,3,2] row_mask:0xf bank_mask:0xf
	v_mov_b32_e32 v3, s64
	v_cndmask_b32_e32 v7, v251, v250, vcc
	s_nop 1
	v_max_u32_dpp v6, v7, v7 row_half_mirror row_mask:0xf bank_mask:0x5
	ds_permute_b32 v2, v10, v2
	v_min_u32_dpp v6, v7, v7 row_half_mirror row_mask:0xf bank_mask:0xa
	s_nop 1
	v_max_u32_dpp v250, v6, v6 quad_perm:[2,3,0,1] row_mask:0xf bank_mask:0xf
	v_min_u32_dpp v251, v6, v6 quad_perm:[2,3,0,1] row_mask:0xf bank_mask:0xf
	v_cndmask_b32_e64 v7, v251, v250, s[48:49]
	s_nop 1
	v_max_u32_dpp v250, v7, v7 quad_perm:[1,0,3,2] row_mask:0xf bank_mask:0xf
	v_min_u32_dpp v251, v7, v7 quad_perm:[1,0,3,2] row_mask:0xf bank_mask:0xf
	v_cndmask_b32_e32 v6, v251, v250, vcc
	s_nop 1
	v_max_u32_dpp v7, v6, v6 row_mirror row_mask:0xf bank_mask:0x3
	v_min_u32_dpp v7, v6, v6 row_mirror row_mask:0xf bank_mask:0xc
	s_nop 1
	v_max_u32_dpp v6, v7, v7 row_ror:12 row_mask:0xf bank_mask:0x5
	v_min_u32_dpp v6, v7, v7 row_ror:4 row_mask:0xf bank_mask:0xa
	s_nop 1
	v_max_u32_dpp v250, v6, v6 quad_perm:[2,3,0,1] row_mask:0xf bank_mask:0xf
	v_min_u32_dpp v251, v6, v6 quad_perm:[2,3,0,1] row_mask:0xf bank_mask:0xf
	v_cndmask_b32_e64 v7, v251, v250, s[48:49]
	s_nop 1
	v_max_u32_dpp v250, v7, v7 quad_perm:[1,0,3,2] row_mask:0xf bank_mask:0xf
	v_min_u32_dpp v251, v7, v7 quad_perm:[1,0,3,2] row_mask:0xf bank_mask:0xf
	v_cndmask_b32_e32 v6, v251, v250, vcc
	s_nop 1
	v_mov_b32_dpp v250, v6 row_mirror row_mask:0xf bank_mask:0xf
	v_mov_b32_e32 v251, v250
	s_nop 0
	s_nop 0
	v_permlane16_swap_b32_e32 v250, v251
	s_nop 1
	v_max_u32_dpp v6, v251, v6 quad_perm:[0,1,2,3] row_mask:0x5 bank_mask:0xf
	v_min_u32_dpp v6, v250, v6 quad_perm:[0,1,2,3] row_mask:0xa bank_mask:0xf
	s_nop 1
	v_max_u32_dpp v7, v6, v6 row_ror:8 row_mask:0xf bank_mask:0x3
	v_min_u32_dpp v7, v6, v6 row_ror:8 row_mask:0xf bank_mask:0xc
	s_nop 1
	v_max_u32_dpp v6, v7, v7 row_ror:12 row_mask:0xf bank_mask:0x5
	v_min_u32_dpp v6, v7, v7 row_ror:4 row_mask:0xf bank_mask:0xa
	s_nop 1
	v_max_u32_dpp v250, v6, v6 quad_perm:[2,3,0,1] row_mask:0xf bank_mask:0xf
	v_min_u32_dpp v251, v6, v6 quad_perm:[2,3,0,1] row_mask:0xf bank_mask:0xf
	v_cndmask_b32_e64 v7, v251, v250, s[48:49]
	s_nop 1
	v_max_u32_dpp v250, v7, v7 quad_perm:[1,0,3,2] row_mask:0xf bank_mask:0xf
	v_min_u32_dpp v251, v7, v7 quad_perm:[1,0,3,2] row_mask:0xf bank_mask:0xf
	v_cndmask_b32_e32 v6, v251, v250, vcc
	s_nop 1
	v_mov_b32_dpp v250, v6 row_mirror row_mask:0xf bank_mask:0xf
	v_mov_b32_e32 v251, v250
	s_nop 1
	v_permlane32_swap_b32_e32 v251, v250
	s_nop 1
	v_max_u32_dpp v6, v250, v6 quad_perm:[0,1,2,3] row_mask:0x1 bank_mask:0xf
	v_min_u32_dpp v6, v251, v6 quad_perm:[0,1,2,3] row_mask:0x4 bank_mask:0xf
	s_nop 1
	v_max_u32_dpp v7, v6, v6 row_ror:8 row_mask:0xf bank_mask:0x3
	v_min_u32_dpp v7, v6, v6 row_ror:8 row_mask:0xf bank_mask:0xc
	s_nop 1
	v_max_u32_dpp v6, v7, v7 row_ror:12 row_mask:0xf bank_mask:0x5
	v_min_u32_dpp v6, v7, v7 row_ror:4 row_mask:0xf bank_mask:0xa
	s_nop 1
	v_max_u32_dpp v250, v6, v6 quad_perm:[2,3,0,1] row_mask:0xf bank_mask:0xf
	v_min_u32_dpp v251, v6, v6 quad_perm:[2,3,0,1] row_mask:0xf bank_mask:0xf
	v_cndmask_b32_e64 v7, v251, v250, s[48:49]
	s_nop 1
	v_max_u32_dpp v250, v7, v7 quad_perm:[1,0,3,2] row_mask:0xf bank_mask:0xf
	v_min_u32_dpp v251, v7, v7 quad_perm:[1,0,3,2] row_mask:0xf bank_mask:0xf
	v_cndmask_b32_e32 v6, v251, v250, vcc
	v_not_b32_e32 v253, v6
	v_and_b32_e32 v253, 63, v253
	v_lshlrev_b32_e32 v253, 2, v253
	ds_permute_b32 v6, v253, v81
	s_waitcnt lgkmcnt(0)
	v_lshlrev_b32_e32 v8, 3, v6
	v_lshlrev_b32_e32 v7, 7, v6
	v_and_b32_e32 v8, 0x70, v8
	v_and_or_b32 v7, v7, s43, v8
	v_cmp_gt_u32_e32 vcc, 16, v6
	v_and_b32_e32 v8, 0x7f, v31
	s_nop 0
	v_cndmask_b32_e32 v6, 4, v7, vcc
	ds_permute_b32 v0, v6, v0
	v_lshlrev_b32_e32 v7, 7, v23
	v_and_or_b32 v7, v7, s44, v8
	s_waitcnt lgkmcnt(0)
	v_readlane_b32 s2, v0, 0
	s_nop 1
	v_subrev_f32_e32 v0, s2, v0
	v_mul_f32_e32 v0, 0x3fb8aa3b, v0
	v_exp_f32_e32 v0, v0
	v_div_scale_f32 v4, s[2:3], v3, v3, v1
	v_rcp_f32_e32 v5, v4
	v_cndmask_b32_e64 v9, 0, v0, s[12:13]
	s_nop 1
	v_add_f32_dpp v254, v9, v9 quad_perm:[1,0,3,2] row_mask:0xf bank_mask:0xf
	s_nop 1
	v_add_f32_dpp v254, v254, v254 quad_perm:[2,3,0,1] row_mask:0xf bank_mask:0xf
	s_nop 1
	v_add_f32_dpp v254, v254, v254 row_half_mirror row_mask:0xf bank_mask:0xf
	s_nop 1
	v_add_f32_dpp v254, v254, v254 row_mirror row_mask:0xf bank_mask:0xf
	s_nop 1
	v_add_f32_dpp v254, v254, v254 row_bcast:15 row_mask:0xa bank_mask:0xf
	s_nop 1
	v_add_f32_dpp v254, v254, v254 row_bcast:31 row_mask:0xc bank_mask:0xf
	s_nop 1
	v_readlane_b32 s65, v254, 63
	v_fma_f32 v10, -v4, v5, 1.0
	v_fmac_f32_e32 v5, v10, v5
	v_div_scale_f32 v10, vcc, v1, v3, v1
	s_waitcnt lgkmcnt(0)
	v_mul_f32_e32 v12, v10, v5
	v_fma_f32 v13, -v4, v12, v10
	v_fmac_f32_e32 v12, v13, v5
	v_fma_f32 v4, -v4, v12, v10
	s_waitcnt lgkmcnt(0)
	v_div_fmas_f32 v4, v4, v5, v12
	s_waitcnt vmcnt(27)
	v_cmp_lt_i32_e32 vcc, -1, v30
	v_div_fixup_f32 v3, v4, v3, v1
	v_and_b32_e32 v4, 0xffffff80, v22
	v_cndmask_b32_e64 v1, v232, -1, vcc
	v_cmp_lt_i32_e32 vcc, -1, v22
	s_waitcnt lgkmcnt(0)
	v_and_b32_e32 v0, 0xffffff80, v30
	v_cndmask_b32_e64 v5, v232, -1, vcc
	s_waitcnt vmcnt(26)
	v_cmp_lt_i32_e32 vcc, -1, v29
	v_xor_b32_e32 v1, v1, v0
	v_xor_b32_e32 v5, v5, v4
	v_cndmask_b32_e64 v11, v232, -1, vcc
	v_cmp_lt_i32_e32 vcc, -1, v24
	v_and_b32_e32 v0, 0xffffff80, v29
	v_and_b32_e32 v4, 0xffffff80, v24
	v_cndmask_b32_e64 v12, v232, -1, vcc
	v_xor_b32_e32 v0, v11, v0
	v_xor_b32_e32 v4, v12, v4
	v_pk_add_f32 v[0:1], v[4:5], v[0:1]
	v_or_b32_e32 v4, 0x80000000, v1
	v_not_b32_e32 v5, v1
	v_cmp_gt_i32_e32 vcc, 0, v1
	s_nop 1
	v_cndmask_b32_e32 v4, v4, v5, vcc
	v_and_b32_e32 v4, 0xffffffc0, v4
	v_cndmask_b32_e64 v4, 0, v4, s[10:11]
	v_bitop3_b32 v4, v4, 63, v81 bitop3:0x36
	s_nop 0
	s_mov_b32 vcc_lo, 0x55555555
	s_mov_b32 vcc_hi, 0x55555555
	s_mov_b32 s48, 0x33333333
	s_mov_b32 s49, 0x33333333
	v_max_u32_dpp v250, v4, v4 quad_perm:[1,0,3,2] row_mask:0xf bank_mask:0xf
	v_min_u32_dpp v251, v4, v4 quad_perm:[1,0,3,2] row_mask:0xf bank_mask:0xf
	v_cndmask_b32_e32 v5, v251, v250, vcc
	s_nop 1
	v_max_u32_dpp v250, v5, v5 quad_perm:[3,2,1,0] row_mask:0xf bank_mask:0xf
	v_min_u32_dpp v251, v5, v5 quad_perm:[3,2,1,0] row_mask:0xf bank_mask:0xf
	v_cndmask_b32_e64 v4, v251, v250, s[48:49]
	s_nop 1
	v_max_u32_dpp v250, v4, v4 quad_perm:[1,0,3,2] row_mask:0xf bank_mask:0xf
	v_min_u32_dpp v251, v4, v4 quad_perm:[1,0,3,2] row_mask:0xf bank_mask:0xf
	v_cndmask_b32_e32 v5, v251, v250, vcc
	s_nop 1
	v_max_u32_dpp v4, v5, v5 row_half_mirror row_mask:0xf bank_mask:0x5
	v_min_u32_dpp v4, v5, v5 row_half_mirror row_mask:0xf bank_mask:0xa
	s_nop 1
	v_max_u32_dpp v250, v4, v4 quad_perm:[2,3,0,1] row_mask:0xf bank_mask:0xf
	v_min_u32_dpp v251, v4, v4 quad_perm:[2,3,0,1] row_mask:0xf bank_mask:0xf
	v_cndmask_b32_e64 v5, v251, v250, s[48:49]
	s_nop 1
	v_max_u32_dpp v250, v5, v5 quad_perm:[1,0,3,2] row_mask:0xf bank_mask:0xf
	v_min_u32_dpp v251, v5, v5 quad_perm:[1,0,3,2] row_mask:0xf bank_mask:0xf
	v_cndmask_b32_e32 v4, v251, v250, vcc
	s_nop 1
	v_max_u32_dpp v5, v4, v4 row_mirror row_mask:0xf bank_mask:0x3
	v_min_u32_dpp v5, v4, v4 row_mirror row_mask:0xf bank_mask:0xc
	s_nop 1
	v_max_u32_dpp v4, v5, v5 row_ror:12 row_mask:0xf bank_mask:0x5
	v_min_u32_dpp v4, v5, v5 row_ror:4 row_mask:0xf bank_mask:0xa
	s_nop 1
	v_max_u32_dpp v250, v4, v4 quad_perm:[2,3,0,1] row_mask:0xf bank_mask:0xf
	v_min_u32_dpp v251, v4, v4 quad_perm:[2,3,0,1] row_mask:0xf bank_mask:0xf
	v_cndmask_b32_e64 v5, v251, v250, s[48:49]
	s_nop 1
	v_max_u32_dpp v250, v5, v5 quad_perm:[1,0,3,2] row_mask:0xf bank_mask:0xf
	v_min_u32_dpp v251, v5, v5 quad_perm:[1,0,3,2] row_mask:0xf bank_mask:0xf
	v_cndmask_b32_e32 v4, v251, v250, vcc
	s_nop 1
	v_mov_b32_dpp v250, v4 row_mirror row_mask:0xf bank_mask:0xf
	v_mov_b32_e32 v251, v250
	s_nop 0
	s_nop 0
	v_permlane16_swap_b32_e32 v250, v251
	s_nop 1
	v_max_u32_dpp v4, v251, v4 quad_perm:[0,1,2,3] row_mask:0x5 bank_mask:0xf
	v_min_u32_dpp v4, v250, v4 quad_perm:[0,1,2,3] row_mask:0xa bank_mask:0xf
	s_nop 1
	v_max_u32_dpp v5, v4, v4 row_ror:8 row_mask:0xf bank_mask:0x3
	v_min_u32_dpp v5, v4, v4 row_ror:8 row_mask:0xf bank_mask:0xc
	s_nop 1
	v_max_u32_dpp v4, v5, v5 row_ror:12 row_mask:0xf bank_mask:0x5
	v_min_u32_dpp v4, v5, v5 row_ror:4 row_mask:0xf bank_mask:0xa
	s_nop 1
	v_max_u32_dpp v250, v4, v4 quad_perm:[2,3,0,1] row_mask:0xf bank_mask:0xf
	v_min_u32_dpp v251, v4, v4 quad_perm:[2,3,0,1] row_mask:0xf bank_mask:0xf
	v_cndmask_b32_e64 v5, v251, v250, s[48:49]
	s_nop 1
	v_max_u32_dpp v250, v5, v5 quad_perm:[1,0,3,2] row_mask:0xf bank_mask:0xf
	v_min_u32_dpp v251, v5, v5 quad_perm:[1,0,3,2] row_mask:0xf bank_mask:0xf
	v_cndmask_b32_e32 v4, v251, v250, vcc
	s_nop 1
	v_mov_b32_dpp v250, v4 row_mirror row_mask:0xf bank_mask:0xf
	v_mov_b32_e32 v251, v250
	s_nop 1
	v_permlane32_swap_b32_e32 v251, v250
	s_nop 1
	v_max_u32_dpp v4, v250, v4 quad_perm:[0,1,2,3] row_mask:0x1 bank_mask:0xf
	v_min_u32_dpp v4, v251, v4 quad_perm:[0,1,2,3] row_mask:0x4 bank_mask:0xf
	s_nop 1
	v_max_u32_dpp v5, v4, v4 row_ror:8 row_mask:0xf bank_mask:0x3
	v_min_u32_dpp v5, v4, v4 row_ror:8 row_mask:0xf bank_mask:0xc
	s_nop 1
	v_max_u32_dpp v4, v5, v5 row_ror:12 row_mask:0xf bank_mask:0x5
	v_min_u32_dpp v4, v5, v5 row_ror:4 row_mask:0xf bank_mask:0xa
	s_nop 1
	v_max_u32_dpp v250, v4, v4 quad_perm:[2,3,0,1] row_mask:0xf bank_mask:0xf
	v_min_u32_dpp v251, v4, v4 quad_perm:[2,3,0,1] row_mask:0xf bank_mask:0xf
	v_cndmask_b32_e64 v5, v251, v250, s[48:49]
	s_nop 1
	v_max_u32_dpp v250, v5, v5 quad_perm:[1,0,3,2] row_mask:0xf bank_mask:0xf
	v_min_u32_dpp v251, v5, v5 quad_perm:[1,0,3,2] row_mask:0xf bank_mask:0xf
	v_cndmask_b32_e32 v4, v251, v250, vcc
	v_not_b32_e32 v253, v4
	v_and_b32_e32 v253, 63, v253
	v_lshlrev_b32_e32 v253, 2, v253
	ds_permute_b32 v4, v253, v81
	s_waitcnt lgkmcnt(0)
	v_lshlrev_b32_e32 v11, 3, v4
	v_lshlrev_b32_e32 v5, 7, v4
	v_and_b32_e32 v11, 0x70, v11
	v_and_or_b32 v5, v5, s43, v11
	v_cmp_gt_u32_e32 vcc, 16, v4
	ds_permute_b32 v4, v6, v7
	s_nop 0
	v_cndmask_b32_e32 v11, 4, v5, vcc
	ds_permute_b32 v1, v11, v1
	s_waitcnt lgkmcnt(2)
	v_mov_b32_e32 v5, s65
	v_div_scale_f32 v8, s[2:3], v5, v5, v9
	v_rcp_f32_e32 v10, v8
	s_waitcnt lgkmcnt(0)
	v_readlane_b32 s2, v1, 0
	v_div_scale_f32 v7, vcc, v9, v5, v9
	s_nop 0
	v_subrev_f32_e32 v1, s2, v1
	v_mul_f32_e32 v1, 0x3fb8aa3b, v1
	v_exp_f32_e32 v1, v1
	v_fma_f32 v6, -v8, v10, 1.0
	v_fmac_f32_e32 v10, v6, v10
	v_mul_f32_e32 v12, v7, v10
	v_cndmask_b32_e64 v1, 0, v1, s[12:13]
	s_nop 1
	v_add_f32_dpp v254, v1, v1 quad_perm:[1,0,3,2] row_mask:0xf bank_mask:0xf
	s_nop 1
	v_add_f32_dpp v254, v254, v254 quad_perm:[2,3,0,1] row_mask:0xf bank_mask:0xf
	s_nop 1
	v_add_f32_dpp v254, v254, v254 row_half_mirror row_mask:0xf bank_mask:0xf
	s_nop 1
	v_add_f32_dpp v254, v254, v254 row_mirror row_mask:0xf bank_mask:0xf
	s_nop 1
	v_add_f32_dpp v254, v254, v254 row_bcast:15 row_mask:0xa bank_mask:0xf
	s_nop 1
	v_add_f32_dpp v254, v254, v254 row_bcast:31 row_mask:0xc bank_mask:0xf
	s_nop 1
	v_readlane_b32 s64, v254, 63
	v_fma_f32 v13, -v8, v12, v7
	v_fmac_f32_e32 v12, v13, v10
	v_fma_f32 v7, -v8, v12, v7
	v_div_fmas_f32 v7, v7, v10, v12
	s_waitcnt lgkmcnt(0)
	v_div_fixup_f32 v5, v7, v5, v9
	ds_write2st64_b64 v239, v[2:3], v[4:5] offset0:2 offset1:3
	v_not_b32_e32 v7, v0
	v_cmp_gt_i32_e32 vcc, 0, v0
	s_waitcnt lgkmcnt(1)
	v_lshlrev_b32_e32 v2, 7, v22
	v_and_b32_e32 v3, 0x7f, v30
	v_and_or_b32 v2, v2, s44, v3
	v_lshlrev_b32_e32 v3, 7, v24
	s_waitcnt lgkmcnt(0)
	v_or_b32_e32 v6, 0x80000000, v0
	v_cndmask_b32_e32 v6, v6, v7, vcc
	v_and_b32_e32 v6, 0xffffffc0, v6
	v_cndmask_b32_e64 v6, 0, v6, s[10:11]
	v_bitop3_b32 v6, v6, 63, v81 bitop3:0x36
	s_mov_b32 vcc_lo, 0x55555555
	s_waitcnt lgkmcnt(0)
	s_mov_b32 vcc_hi, 0x55555555
	v_mov_b32_e32 v4, s64
	s_mov_b32 s48, 0x33333333
	s_mov_b32 s49, 0x33333333
	v_max_u32_dpp v250, v6, v6 quad_perm:[1,0,3,2] row_mask:0xf bank_mask:0xf
	v_min_u32_dpp v251, v6, v6 quad_perm:[1,0,3,2] row_mask:0xf bank_mask:0xf
	v_cndmask_b32_e32 v7, v251, v250, vcc
	s_nop 1
	v_max_u32_dpp v250, v7, v7 quad_perm:[3,2,1,0] row_mask:0xf bank_mask:0xf
	v_min_u32_dpp v251, v7, v7 quad_perm:[3,2,1,0] row_mask:0xf bank_mask:0xf
	v_cndmask_b32_e64 v6, v251, v250, s[48:49]
	s_nop 1
	v_max_u32_dpp v250, v6, v6 quad_perm:[1,0,3,2] row_mask:0xf bank_mask:0xf
	v_min_u32_dpp v251, v6, v6 quad_perm:[1,0,3,2] row_mask:0xf bank_mask:0xf
	v_cndmask_b32_e32 v7, v251, v250, vcc
	s_nop 1
	v_max_u32_dpp v6, v7, v7 row_half_mirror row_mask:0xf bank_mask:0x5
	v_min_u32_dpp v6, v7, v7 row_half_mirror row_mask:0xf bank_mask:0xa
	s_nop 1
	v_max_u32_dpp v250, v6, v6 quad_perm:[2,3,0,1] row_mask:0xf bank_mask:0xf
	v_min_u32_dpp v251, v6, v6 quad_perm:[2,3,0,1] row_mask:0xf bank_mask:0xf
	v_cndmask_b32_e64 v7, v251, v250, s[48:49]
	s_nop 1
	v_max_u32_dpp v250, v7, v7 quad_perm:[1,0,3,2] row_mask:0xf bank_mask:0xf
	v_min_u32_dpp v251, v7, v7 quad_perm:[1,0,3,2] row_mask:0xf bank_mask:0xf
	v_cndmask_b32_e32 v6, v251, v250, vcc
	s_nop 1
	v_max_u32_dpp v7, v6, v6 row_mirror row_mask:0xf bank_mask:0x3
	v_min_u32_dpp v7, v6, v6 row_mirror row_mask:0xf bank_mask:0xc
	s_nop 1
	v_max_u32_dpp v6, v7, v7 row_ror:12 row_mask:0xf bank_mask:0x5
	v_min_u32_dpp v6, v7, v7 row_ror:4 row_mask:0xf bank_mask:0xa
	s_nop 1
	v_max_u32_dpp v250, v6, v6 quad_perm:[2,3,0,1] row_mask:0xf bank_mask:0xf
	v_min_u32_dpp v251, v6, v6 quad_perm:[2,3,0,1] row_mask:0xf bank_mask:0xf
	v_cndmask_b32_e64 v7, v251, v250, s[48:49]
	s_nop 1
	v_max_u32_dpp v250, v7, v7 quad_perm:[1,0,3,2] row_mask:0xf bank_mask:0xf
	v_min_u32_dpp v251, v7, v7 quad_perm:[1,0,3,2] row_mask:0xf bank_mask:0xf
	v_cndmask_b32_e32 v6, v251, v250, vcc
	s_nop 1
	v_mov_b32_dpp v250, v6 row_mirror row_mask:0xf bank_mask:0xf
	v_mov_b32_e32 v251, v250
	s_nop 0
	s_nop 0
	v_permlane16_swap_b32_e32 v250, v251
	s_nop 1
	v_max_u32_dpp v6, v251, v6 quad_perm:[0,1,2,3] row_mask:0x5 bank_mask:0xf
	v_min_u32_dpp v6, v250, v6 quad_perm:[0,1,2,3] row_mask:0xa bank_mask:0xf
	s_nop 1
	v_max_u32_dpp v7, v6, v6 row_ror:8 row_mask:0xf bank_mask:0x3
	v_min_u32_dpp v7, v6, v6 row_ror:8 row_mask:0xf bank_mask:0xc
	s_nop 1
	v_max_u32_dpp v6, v7, v7 row_ror:12 row_mask:0xf bank_mask:0x5
	v_min_u32_dpp v6, v7, v7 row_ror:4 row_mask:0xf bank_mask:0xa
	s_nop 1
	v_max_u32_dpp v250, v6, v6 quad_perm:[2,3,0,1] row_mask:0xf bank_mask:0xf
	v_min_u32_dpp v251, v6, v6 quad_perm:[2,3,0,1] row_mask:0xf bank_mask:0xf
	v_cndmask_b32_e64 v7, v251, v250, s[48:49]
	s_nop 1
	v_max_u32_dpp v250, v7, v7 quad_perm:[1,0,3,2] row_mask:0xf bank_mask:0xf
	v_min_u32_dpp v251, v7, v7 quad_perm:[1,0,3,2] row_mask:0xf bank_mask:0xf
	v_cndmask_b32_e32 v6, v251, v250, vcc
	s_nop 1
	v_mov_b32_dpp v250, v6 row_mirror row_mask:0xf bank_mask:0xf
	v_mov_b32_e32 v251, v250
	s_nop 1
	v_permlane32_swap_b32_e32 v251, v250
	s_nop 1
	v_max_u32_dpp v6, v250, v6 quad_perm:[0,1,2,3] row_mask:0x1 bank_mask:0xf
	v_min_u32_dpp v6, v251, v6 quad_perm:[0,1,2,3] row_mask:0x4 bank_mask:0xf
	s_nop 1
	v_max_u32_dpp v7, v6, v6 row_ror:8 row_mask:0xf bank_mask:0x3
	v_min_u32_dpp v7, v6, v6 row_ror:8 row_mask:0xf bank_mask:0xc
	s_nop 1
	v_max_u32_dpp v6, v7, v7 row_ror:12 row_mask:0xf bank_mask:0x5
	v_min_u32_dpp v6, v7, v7 row_ror:4 row_mask:0xf bank_mask:0xa
	s_nop 1
	v_max_u32_dpp v250, v6, v6 quad_perm:[2,3,0,1] row_mask:0xf bank_mask:0xf
	v_min_u32_dpp v251, v6, v6 quad_perm:[2,3,0,1] row_mask:0xf bank_mask:0xf
	v_cndmask_b32_e64 v7, v251, v250, s[48:49]
	s_nop 1
	v_max_u32_dpp v250, v7, v7 quad_perm:[1,0,3,2] row_mask:0xf bank_mask:0xf
	v_min_u32_dpp v251, v7, v7 quad_perm:[1,0,3,2] row_mask:0xf bank_mask:0xf
	v_cndmask_b32_e32 v6, v251, v250, vcc
	v_not_b32_e32 v253, v6
	v_and_b32_e32 v253, 63, v253
	v_lshlrev_b32_e32 v253, 2, v253
	ds_permute_b32 v6, v253, v81
	s_waitcnt lgkmcnt(0)
	v_lshlrev_b32_e32 v8, 3, v6
	v_lshlrev_b32_e32 v7, 7, v6
	v_and_b32_e32 v8, 0x70, v8
	v_and_or_b32 v7, v7, s43, v8
	v_cmp_gt_u32_e32 vcc, 16, v6
	s_nop 1
	v_cndmask_b32_e32 v6, 4, v7, vcc
	ds_permute_b32 v0, v6, v0
	v_and_b32_e32 v7, 0x7f, v29
	v_and_or_b32 v7, v3, s44, v7
	s_waitcnt lgkmcnt(0)
	v_readlane_b32 s2, v0, 0
	s_nop 1
	v_subrev_f32_e32 v0, s2, v0
	v_mul_f32_e32 v0, 0x3fb8aa3b, v0
	v_exp_f32_e32 v5, v0
	ds_permute_b32 v0, v11, v2
	v_div_scale_f32 v8, s[2:3], v4, v4, v1
	v_cndmask_b32_e64 v10, 0, v5, s[12:13]
	s_nop 1
	v_add_f32_dpp v254, v10, v10 quad_perm:[1,0,3,2] row_mask:0xf bank_mask:0xf
	s_nop 1
	v_add_f32_dpp v254, v254, v254 quad_perm:[2,3,0,1] row_mask:0xf bank_mask:0xf
	s_nop 1
	v_add_f32_dpp v254, v254, v254 row_half_mirror row_mask:0xf bank_mask:0xf
	s_nop 1
	v_add_f32_dpp v254, v254, v254 row_mirror row_mask:0xf bank_mask:0xf
	s_nop 1
	v_add_f32_dpp v254, v254, v254 row_bcast:15 row_mask:0xa bank_mask:0xf
	s_nop 1
	v_add_f32_dpp v254, v254, v254 row_bcast:31 row_mask:0xc bank_mask:0xf
	s_nop 1
	v_readlane_b32 s65, v254, 63
	v_rcp_f32_e32 v9, v8
	s_waitcnt lgkmcnt(0)
	v_fma_f32 v5, -v8, v9, 1.0
	v_fmac_f32_e32 v9, v5, v9
	v_div_scale_f32 v5, vcc, v1, v4, v1
	v_mul_f32_e32 v12, v5, v9
	v_fma_f32 v13, -v8, v12, v5
	v_fmac_f32_e32 v12, v13, v9
	s_waitcnt lgkmcnt(0)
	v_fma_f32 v5, -v8, v12, v5
	v_div_fmas_f32 v5, v5, v9, v12
	s_waitcnt vmcnt(25)
	v_cmp_lt_i32_e32 vcc, -1, v19
	v_div_fixup_f32 v1, v5, v4, v1
	v_and_b32_e32 v4, 0xffffff80, v20
	v_cndmask_b32_e64 v3, v232, -1, vcc
	v_cmp_lt_i32_e32 vcc, -1, v20
	s_waitcnt lgkmcnt(0)
	v_and_b32_e32 v2, 0xffffff80, v19
	v_cndmask_b32_e64 v5, v232, -1, vcc
	s_waitcnt vmcnt(24)
	v_cmp_lt_i32_e32 vcc, -1, v16
	v_xor_b32_e32 v3, v3, v2
	v_xor_b32_e32 v5, v5, v4
	v_cndmask_b32_e64 v11, v232, -1, vcc
	v_cmp_lt_i32_e32 vcc, -1, v18
	v_and_b32_e32 v2, 0xffffff80, v16
	v_and_b32_e32 v4, 0xffffff80, v18
	v_cndmask_b32_e64 v12, v232, -1, vcc
	v_xor_b32_e32 v2, v11, v2
	v_xor_b32_e32 v4, v12, v4
	v_pk_add_f32 v[2:3], v[4:5], v[2:3]
	v_or_b32_e32 v4, 0x80000000, v3
	v_not_b32_e32 v5, v3
	v_cmp_gt_i32_e32 vcc, 0, v3
	s_nop 1
	v_cndmask_b32_e32 v4, v4, v5, vcc
	v_and_b32_e32 v4, 0xffffffc0, v4
	v_cndmask_b32_e64 v4, 0, v4, s[10:11]
	v_bitop3_b32 v4, v4, 63, v81 bitop3:0x36
	s_nop 0
	s_mov_b32 vcc_lo, 0x55555555
	s_mov_b32 vcc_hi, 0x55555555
	s_mov_b32 s48, 0x33333333
	s_mov_b32 s49, 0x33333333
	v_max_u32_dpp v250, v4, v4 quad_perm:[1,0,3,2] row_mask:0xf bank_mask:0xf
	v_min_u32_dpp v251, v4, v4 quad_perm:[1,0,3,2] row_mask:0xf bank_mask:0xf
	v_cndmask_b32_e32 v5, v251, v250, vcc
	s_nop 1
	v_max_u32_dpp v250, v5, v5 quad_perm:[3,2,1,0] row_mask:0xf bank_mask:0xf
	v_min_u32_dpp v251, v5, v5 quad_perm:[3,2,1,0] row_mask:0xf bank_mask:0xf
	v_cndmask_b32_e64 v4, v251, v250, s[48:49]
	s_nop 1
	v_max_u32_dpp v250, v4, v4 quad_perm:[1,0,3,2] row_mask:0xf bank_mask:0xf
	v_min_u32_dpp v251, v4, v4 quad_perm:[1,0,3,2] row_mask:0xf bank_mask:0xf
	v_cndmask_b32_e32 v5, v251, v250, vcc
	s_nop 1
	v_max_u32_dpp v4, v5, v5 row_half_mirror row_mask:0xf bank_mask:0x5
	v_min_u32_dpp v4, v5, v5 row_half_mirror row_mask:0xf bank_mask:0xa
	s_nop 1
	v_max_u32_dpp v250, v4, v4 quad_perm:[2,3,0,1] row_mask:0xf bank_mask:0xf
	v_min_u32_dpp v251, v4, v4 quad_perm:[2,3,0,1] row_mask:0xf bank_mask:0xf
	v_cndmask_b32_e64 v5, v251, v250, s[48:49]
	s_nop 1
	v_max_u32_dpp v250, v5, v5 quad_perm:[1,0,3,2] row_mask:0xf bank_mask:0xf
	v_min_u32_dpp v251, v5, v5 quad_perm:[1,0,3,2] row_mask:0xf bank_mask:0xf
	v_cndmask_b32_e32 v4, v251, v250, vcc
	s_nop 1
	v_max_u32_dpp v5, v4, v4 row_mirror row_mask:0xf bank_mask:0x3
	v_min_u32_dpp v5, v4, v4 row_mirror row_mask:0xf bank_mask:0xc
	s_nop 1
	v_max_u32_dpp v4, v5, v5 row_ror:12 row_mask:0xf bank_mask:0x5
	v_min_u32_dpp v4, v5, v5 row_ror:4 row_mask:0xf bank_mask:0xa
	s_nop 1
	v_max_u32_dpp v250, v4, v4 quad_perm:[2,3,0,1] row_mask:0xf bank_mask:0xf
	v_min_u32_dpp v251, v4, v4 quad_perm:[2,3,0,1] row_mask:0xf bank_mask:0xf
	v_cndmask_b32_e64 v5, v251, v250, s[48:49]
	s_nop 1
	v_max_u32_dpp v250, v5, v5 quad_perm:[1,0,3,2] row_mask:0xf bank_mask:0xf
	v_min_u32_dpp v251, v5, v5 quad_perm:[1,0,3,2] row_mask:0xf bank_mask:0xf
	v_cndmask_b32_e32 v4, v251, v250, vcc
	s_nop 1
	v_mov_b32_dpp v250, v4 row_mirror row_mask:0xf bank_mask:0xf
	v_mov_b32_e32 v251, v250
	s_nop 0
	s_nop 0
	v_permlane16_swap_b32_e32 v250, v251
	s_nop 1
	v_max_u32_dpp v4, v251, v4 quad_perm:[0,1,2,3] row_mask:0x5 bank_mask:0xf
	v_min_u32_dpp v4, v250, v4 quad_perm:[0,1,2,3] row_mask:0xa bank_mask:0xf
	s_nop 1
	v_max_u32_dpp v5, v4, v4 row_ror:8 row_mask:0xf bank_mask:0x3
	v_min_u32_dpp v5, v4, v4 row_ror:8 row_mask:0xf bank_mask:0xc
	s_nop 1
	v_max_u32_dpp v4, v5, v5 row_ror:12 row_mask:0xf bank_mask:0x5
	v_min_u32_dpp v4, v5, v5 row_ror:4 row_mask:0xf bank_mask:0xa
	s_nop 1
	v_max_u32_dpp v250, v4, v4 quad_perm:[2,3,0,1] row_mask:0xf bank_mask:0xf
	v_min_u32_dpp v251, v4, v4 quad_perm:[2,3,0,1] row_mask:0xf bank_mask:0xf
	v_cndmask_b32_e64 v5, v251, v250, s[48:49]
	s_nop 1
	v_max_u32_dpp v250, v5, v5 quad_perm:[1,0,3,2] row_mask:0xf bank_mask:0xf
	v_min_u32_dpp v251, v5, v5 quad_perm:[1,0,3,2] row_mask:0xf bank_mask:0xf
	v_cndmask_b32_e32 v4, v251, v250, vcc
	s_nop 1
	v_mov_b32_dpp v250, v4 row_mirror row_mask:0xf bank_mask:0xf
	v_mov_b32_e32 v251, v250
	s_nop 1
	v_permlane32_swap_b32_e32 v251, v250
	s_nop 1
	v_max_u32_dpp v4, v250, v4 quad_perm:[0,1,2,3] row_mask:0x1 bank_mask:0xf
	v_min_u32_dpp v4, v251, v4 quad_perm:[0,1,2,3] row_mask:0x4 bank_mask:0xf
	s_nop 1
	v_max_u32_dpp v5, v4, v4 row_ror:8 row_mask:0xf bank_mask:0x3
	v_min_u32_dpp v5, v4, v4 row_ror:8 row_mask:0xf bank_mask:0xc
	s_nop 1
	v_max_u32_dpp v4, v5, v5 row_ror:12 row_mask:0xf bank_mask:0x5
	v_min_u32_dpp v4, v5, v5 row_ror:4 row_mask:0xf bank_mask:0xa
	s_nop 1
	v_max_u32_dpp v250, v4, v4 quad_perm:[2,3,0,1] row_mask:0xf bank_mask:0xf
	v_min_u32_dpp v251, v4, v4 quad_perm:[2,3,0,1] row_mask:0xf bank_mask:0xf
	v_cndmask_b32_e64 v5, v251, v250, s[48:49]
	s_nop 1
	v_max_u32_dpp v250, v5, v5 quad_perm:[1,0,3,2] row_mask:0xf bank_mask:0xf
	v_min_u32_dpp v251, v5, v5 quad_perm:[1,0,3,2] row_mask:0xf bank_mask:0xf
	v_cndmask_b32_e32 v4, v251, v250, vcc
	v_not_b32_e32 v253, v4
	v_and_b32_e32 v253, 63, v253
	v_lshlrev_b32_e32 v253, 2, v253
	ds_permute_b32 v4, v253, v81
	s_waitcnt lgkmcnt(0)
	v_lshlrev_b32_e32 v11, 3, v4
	v_lshlrev_b32_e32 v5, 7, v4
	v_and_b32_e32 v11, 0x70, v11
	v_and_or_b32 v5, v5, s43, v11
	v_cmp_gt_u32_e32 vcc, 16, v4
	ds_permute_b32 v4, v6, v7
	s_nop 0
	v_cndmask_b32_e32 v11, 4, v5, vcc
	s_waitcnt lgkmcnt(1)
	v_mov_b32_e32 v5, s65
	v_div_scale_f32 v8, s[2:3], v5, v5, v10
	v_rcp_f32_e32 v9, v8
	v_div_scale_f32 v7, vcc, v10, v5, v10
	ds_permute_b32 v3, v11, v3
	v_fma_f32 v6, -v8, v9, 1.0
	v_fmac_f32_e32 v9, v6, v9
	v_mul_f32_e32 v12, v7, v9
	v_fma_f32 v13, -v8, v12, v7
	v_fmac_f32_e32 v12, v13, v9
	v_fma_f32 v7, -v8, v12, v7
	v_div_fmas_f32 v7, v7, v9, v12
	v_or_b32_e32 v8, 0x80000000, v2
	v_not_b32_e32 v9, v2
	v_cmp_gt_i32_e32 vcc, 0, v2
	s_waitcnt lgkmcnt(0)
	v_readlane_b32 s2, v3, 0
	v_div_fixup_f32 v5, v7, v5, v10
	v_cndmask_b32_e32 v8, v8, v9, vcc
	v_and_b32_e32 v8, 0xffffffc0, v8
	v_cndmask_b32_e64 v8, 0, v8, s[10:11]
	v_bitop3_b32 v8, v8, 63, v81 bitop3:0x36
	v_subrev_f32_e32 v3, s2, v3
	s_mov_b32 vcc_lo, 0x55555555
	v_mul_f32_e32 v3, 0x3fb8aa3b, v3
	v_exp_f32_e32 v3, v3
	s_mov_b32 vcc_hi, 0x55555555
	s_mov_b32 s48, 0x33333333
	s_mov_b32 s49, 0x33333333
	ds_write2st64_b64 v239, v[0:1], v[4:5] offset0:4 offset1:5
	v_max_u32_dpp v250, v8, v8 quad_perm:[1,0,3,2] row_mask:0xf bank_mask:0xf
	v_min_u32_dpp v251, v8, v8 quad_perm:[1,0,3,2] row_mask:0xf bank_mask:0xf
	v_cndmask_b32_e32 v9, v251, v250, vcc
	v_cndmask_b32_e64 v3, 0, v3, s[12:13]
	s_nop 1
	v_add_f32_dpp v254, v3, v3 quad_perm:[1,0,3,2] row_mask:0xf bank_mask:0xf
	s_nop 1
	v_add_f32_dpp v254, v254, v254 quad_perm:[2,3,0,1] row_mask:0xf bank_mask:0xf
	s_nop 1
	v_add_f32_dpp v254, v254, v254 row_half_mirror row_mask:0xf bank_mask:0xf
	s_nop 1
	v_add_f32_dpp v254, v254, v254 row_mirror row_mask:0xf bank_mask:0xf
	s_nop 1
	v_add_f32_dpp v254, v254, v254 row_bcast:15 row_mask:0xa bank_mask:0xf
	s_nop 1
	v_add_f32_dpp v254, v254, v254 row_bcast:31 row_mask:0xc bank_mask:0xf
	s_nop 1
	v_readlane_b32 s64, v254, 63
	s_nop 1
	v_max_u32_dpp v250, v9, v9 quad_perm:[3,2,1,0] row_mask:0xf bank_mask:0xf
	v_min_u32_dpp v251, v9, v9 quad_perm:[3,2,1,0] row_mask:0xf bank_mask:0xf
	v_cndmask_b32_e64 v8, v251, v250, s[48:49]
	s_nop 1
	v_max_u32_dpp v250, v8, v8 quad_perm:[1,0,3,2] row_mask:0xf bank_mask:0xf
	v_lshlrev_b32_e32 v0, 7, v20
	v_min_u32_dpp v251, v8, v8 quad_perm:[1,0,3,2] row_mask:0xf bank_mask:0xf
	v_cndmask_b32_e32 v9, v251, v250, vcc
	s_nop 1
	s_waitcnt lgkmcnt(0)
	v_max_u32_dpp v8, v9, v9 row_half_mirror row_mask:0xf bank_mask:0x5
	v_min_u32_dpp v8, v9, v9 row_half_mirror row_mask:0xf bank_mask:0xa
	s_nop 1
	v_max_u32_dpp v250, v8, v8 quad_perm:[2,3,0,1] row_mask:0xf bank_mask:0xf
	v_min_u32_dpp v251, v8, v8 quad_perm:[2,3,0,1] row_mask:0xf bank_mask:0xf
	v_cndmask_b32_e64 v9, v251, v250, s[48:49]
	s_waitcnt lgkmcnt(0)
	s_nop 1
	v_max_u32_dpp v250, v9, v9 quad_perm:[1,0,3,2] row_mask:0xf bank_mask:0xf
	v_min_u32_dpp v251, v9, v9 quad_perm:[1,0,3,2] row_mask:0xf bank_mask:0xf
	v_cndmask_b32_e32 v8, v251, v250, vcc
	s_nop 1
	v_max_u32_dpp v9, v8, v8 row_mirror row_mask:0xf bank_mask:0x3
	v_min_u32_dpp v9, v8, v8 row_mirror row_mask:0xf bank_mask:0xc
	v_and_b32_e32 v1, 0x7f, v19
	s_nop 1
	v_max_u32_dpp v8, v9, v9 row_ror:12 row_mask:0xf bank_mask:0x5
	v_min_u32_dpp v8, v9, v9 row_ror:4 row_mask:0xf bank_mask:0xa
	s_waitcnt lgkmcnt(0)
	s_nop 1
	v_max_u32_dpp v250, v8, v8 quad_perm:[2,3,0,1] row_mask:0xf bank_mask:0xf
	v_min_u32_dpp v251, v8, v8 quad_perm:[2,3,0,1] row_mask:0xf bank_mask:0xf
	v_cndmask_b32_e64 v9, v251, v250, s[48:49]
	v_and_or_b32 v0, v0, s44, v1
	s_nop 1
	v_max_u32_dpp v250, v9, v9 quad_perm:[1,0,3,2] row_mask:0xf bank_mask:0xf
	v_min_u32_dpp v251, v9, v9 quad_perm:[1,0,3,2] row_mask:0xf bank_mask:0xf
	v_cndmask_b32_e32 v8, v251, v250, vcc
	s_nop 1
	v_mov_b32_dpp v250, v8 row_mirror row_mask:0xf bank_mask:0xf
	ds_permute_b32 v0, v11, v0
	v_mov_b32_e32 v251, v250
	s_nop 0
	v_lshlrev_b32_e32 v6, 7, v18
	s_nop 0
	v_permlane16_swap_b32_e32 v250, v251
	s_nop 1
	v_max_u32_dpp v8, v251, v8 quad_perm:[0,1,2,3] row_mask:0x5 bank_mask:0xf
	v_min_u32_dpp v8, v250, v8 quad_perm:[0,1,2,3] row_mask:0xa bank_mask:0xf
	s_nop 1
	v_max_u32_dpp v9, v8, v8 row_ror:8 row_mask:0xf bank_mask:0x3
	v_min_u32_dpp v9, v8, v8 row_ror:8 row_mask:0xf bank_mask:0xc
	s_nop 1
	v_max_u32_dpp v8, v9, v9 row_ror:12 row_mask:0xf bank_mask:0x5
	v_min_u32_dpp v8, v9, v9 row_ror:4 row_mask:0xf bank_mask:0xa
	s_nop 1
	v_max_u32_dpp v250, v8, v8 quad_perm:[2,3,0,1] row_mask:0xf bank_mask:0xf
	v_min_u32_dpp v251, v8, v8 quad_perm:[2,3,0,1] row_mask:0xf bank_mask:0xf
	v_cndmask_b32_e64 v9, v251, v250, s[48:49]
	s_nop 1
	v_max_u32_dpp v250, v9, v9 quad_perm:[1,0,3,2] row_mask:0xf bank_mask:0xf
	v_min_u32_dpp v251, v9, v9 quad_perm:[1,0,3,2] row_mask:0xf bank_mask:0xf
	v_cndmask_b32_e32 v8, v251, v250, vcc
	s_nop 1
	v_mov_b32_dpp v250, v8 row_mirror row_mask:0xf bank_mask:0xf
	v_mov_b32_e32 v251, v250
	s_nop 1
	v_permlane32_swap_b32_e32 v251, v250
	s_nop 1
	v_max_u32_dpp v8, v250, v8 quad_perm:[0,1,2,3] row_mask:0x1 bank_mask:0xf
	v_min_u32_dpp v8, v251, v8 quad_perm:[0,1,2,3] row_mask:0x4 bank_mask:0xf
	s_nop 1
	v_max_u32_dpp v9, v8, v8 row_ror:8 row_mask:0xf bank_mask:0x3
	v_min_u32_dpp v9, v8, v8 row_ror:8 row_mask:0xf bank_mask:0xc
	s_nop 1
	v_max_u32_dpp v8, v9, v9 row_ror:12 row_mask:0xf bank_mask:0x5
	v_min_u32_dpp v8, v9, v9 row_ror:4 row_mask:0xf bank_mask:0xa
	s_nop 1
	v_max_u32_dpp v250, v8, v8 quad_perm:[2,3,0,1] row_mask:0xf bank_mask:0xf
	v_min_u32_dpp v251, v8, v8 quad_perm:[2,3,0,1] row_mask:0xf bank_mask:0xf
	v_cndmask_b32_e64 v9, v251, v250, s[48:49]
	s_nop 1
	v_max_u32_dpp v250, v9, v9 quad_perm:[1,0,3,2] row_mask:0xf bank_mask:0xf
	v_min_u32_dpp v251, v9, v9 quad_perm:[1,0,3,2] row_mask:0xf bank_mask:0xf
	v_cndmask_b32_e32 v8, v251, v250, vcc
	v_not_b32_e32 v253, v8
	v_and_b32_e32 v253, 63, v253
	v_lshlrev_b32_e32 v253, 2, v253
	ds_permute_b32 v8, v253, v81
	s_waitcnt lgkmcnt(0)
	v_lshlrev_b32_e32 v10, 3, v8
	v_lshlrev_b32_e32 v9, 7, v8
	v_and_b32_e32 v10, 0x70, v10
	v_and_or_b32 v9, v9, s43, v10
	v_cmp_gt_u32_e32 vcc, 16, v8
	v_and_b32_e32 v10, 0x7f, v16
	s_nop 0
	v_cndmask_b32_e32 v8, 4, v9, vcc
	ds_permute_b32 v2, v8, v2
	s_waitcnt lgkmcnt(0)
	v_readlane_b32 s2, v2, 0
	s_nop 1
	v_subrev_f32_e32 v2, s2, v2
	v_mul_f32_e32 v2, 0x3fb8aa3b, v2
	v_exp_f32_e32 v2, v2
	s_nop 0
	v_cndmask_b32_e64 v7, 0, v2, s[12:13]
	s_nop 1
	v_add_f32_dpp v254, v7, v7 quad_perm:[1,0,3,2] row_mask:0xf bank_mask:0xf
	s_nop 1
	v_add_f32_dpp v254, v254, v254 quad_perm:[2,3,0,1] row_mask:0xf bank_mask:0xf
	s_nop 1
	v_add_f32_dpp v254, v254, v254 row_half_mirror row_mask:0xf bank_mask:0xf
	s_nop 1
	v_add_f32_dpp v254, v254, v254 row_mirror row_mask:0xf bank_mask:0xf
	s_nop 1
	v_add_f32_dpp v254, v254, v254 row_bcast:15 row_mask:0xa bank_mask:0xf
	s_nop 1
	v_add_f32_dpp v254, v254, v254 row_bcast:31 row_mask:0xc bank_mask:0xf
	s_nop 1
	v_readlane_b32 s65, v254, 63
	v_mov_b32_e32 v2, s64
	v_div_scale_f32 v4, s[2:3], v2, v2, v3
	v_rcp_f32_e32 v5, v4
	s_waitcnt lgkmcnt(0)
	v_fma_f32 v11, -v4, v5, 1.0
	v_fmac_f32_e32 v5, v11, v5
	v_div_scale_f32 v11, vcc, v3, v2, v3
	s_waitcnt lgkmcnt(0)
	v_mul_f32_e32 v12, v11, v5
	v_fma_f32 v13, -v4, v12, v11
	v_fmac_f32_e32 v12, v13, v5
	v_fma_f32 v4, -v4, v12, v11
	s_waitcnt lgkmcnt(0)
	v_div_fmas_f32 v4, v4, v5, v12
	s_waitcnt lgkmcnt(0)
	v_mov_b32_e32 v5, s65
	v_div_scale_f32 v9, s[2:3], v5, v5, v7
	v_rcp_f32_e32 v11, v9
	v_div_fixup_f32 v1, v4, v2, v3
	v_and_or_b32 v2, v6, s44, v10
	ds_permute_b32 v2, v8, v2
	v_fma_f32 v3, -v9, v11, 1.0
	v_fmac_f32_e32 v11, v3, v11
	v_div_scale_f32 v3, vcc, v7, v5, v7
	v_mul_f32_e32 v4, v3, v11
	v_fma_f32 v6, -v9, v4, v3
	v_fmac_f32_e32 v4, v6, v11
	v_fma_f32 v3, -v9, v4, v3
	v_div_fmas_f32 v3, v3, v11, v4
	v_div_fixup_f32 v3, v3, v5, v7
	s_waitcnt lgkmcnt(0)
	ds_write2st64_b64 v239, v[0:1], v[2:3] offset0:6 offset1:7
	s_branch .LBB0_330
